# v38 + one static s_setprio 1 for waves 4-7 at kernel entry
# baseline (speedup 1.0000x reference)
; DI unsigned xb_add(unsigned* p, unsigned v) { return __hip_atomic_fetch_add(p, v, __ATOMIC_RELAXED, __HIP_MEMORY_SCOPE_AGENT); }
; DI unsigned xb_xcc_id() { return (unsigned)__builtin_amdgcn_s_getreg((3 << 11) | 20) & 0xFu; }
; __global__ void __launch_bounds__(NTHR, 4) mega(Params p) {
;   __shared__ __attribute__((aligned(16))) char smem[SMEM_BYTES];
;   cg::grid_group grid = cg::this_grid();
;   const int wv_ = __builtin_amdgcn_readfirstlane((int)threadIdx.x >> 6);
;   unsigned gen = 0u;
;   {
;     const int t0_ = wv_ * 64 + (int)__builtin_amdgcn_mbcnt_hi(~0u, __builtin_amdgcn_mbcnt_lo(~0u, 0u));
;     if (t0_ == 0) {
;       volatile unsigned* st = (volatile unsigned*)(smem + SMEM_BYTES - 32);
;       const unsigned x = xb_xcc_id();
;       st[0] = 0u; st[1] = 0u; st[2] = x;
;       (void)xb_add(&p.bar[XB_XCNT(x)], 1u);
;     }
_Z4mega6Params:
	s_load_dwordx4 s[4:7], s[0:1], 0xe0
	s_load_dwordx16 s[52:67], s[0:1], 0x0
	s_load_dwordx16 s[36:51], s[0:1], 0x40
	s_load_dwordx8 s[84:91], s[0:1], 0xc0
	s_load_dword s17, s[0:1], 0xf0
	v_and_b32_e32 v1, 0x3ff, v0
	v_mbcnt_lo_u32_b32 v2, -1, 0
	s_waitcnt lgkmcnt(0)
	v_writelane_b32 v127, s4, 0
	s_add_u32 s12, s0, 0xf0
	v_readfirstlane_b32 s33, v1
	v_writelane_b32 v127, s5, 1
	v_mbcnt_hi_u32_b32 v2, -1, v2
	s_addc_u32 s13, s1, 0
	v_writelane_b32 v127, s6, 2
	s_andn2_b32 s33, s33, 63
	s_cmp_lt_u32 s33, 0x100
	s_cbranch_scc1 .Lprio_skip
	s_setprio 1
.Lprio_skip:
	v_sub_u32_e32 v2, 0, v2
	s_mov_b32 s16, s2
	v_writelane_b32 v127, s7, 3
	s_mov_b32 s8, 0
	v_cmp_eq_u32_e64 s[2:3], s33, v2
	s_and_saveexec_b64 s[4:5], s[2:3]
	s_cbranch_execz .LBB0_3
	s_mov_b64 s[10:11], src_shared_base
	s_getreg_b32 s9, hwreg(HW_REG_XCC_ID, 0, 4)
	v_mov_b32_e32 v2, 0x12fe0
	v_mov_b32_e32 v3, s11
	v_mov_b32_e32 v4, 0
	s_and_b32 s9, s9, 15
	flat_store_dword v[2:3], v4 sc0 sc1
	s_waitcnt vmcnt(0)
	v_mov_b32_e32 v2, 0x12fe4
	s_mov_b64 s[6:7], exec
	flat_store_dword v[2:3], v4 sc0 sc1
	s_waitcnt vmcnt(0)
	v_mov_b32_e32 v2, 0x12fe8
	v_mov_b32_e32 v4, s9
	flat_store_dword v[2:3], v4 sc0 sc1
	s_waitcnt vmcnt(0)
	v_mbcnt_lo_u32_b32 v2, s6, 0
	v_mbcnt_hi_u32_b32 v2, s7, v2
	v_cmp_eq_u32_e32 vcc, 0, v2
	s_and_b64 s[10:11], exec, vcc
	s_mov_b64 exec, s[10:11]
	s_cbranch_execz .LBB0_3
	s_load_dwordx4 s[20:23], s[0:1], 0xe0
	s_lshl_b32 s9, s9, 8
	s_bcnt1_i32_b64 s6, s[6:7]
	v_mov_b32_e32 v2, s9
	v_mov_b32_e32 v3, s6
	s_waitcnt lgkmcnt(0)
	global_atomic_add v2, v3, s[22:23] offset:1024
